# nt on the attention Q-row loads (each row read once by one wave)
# baseline (speedup 1.0000x reference)
; #define LAS __attribute__((address_space(3)))
; #define DMA_TILE(t, ks, vs) do { glds16(ksrc + (long)(t) * KVBLK * KNP, (unsigned)__builtin_amdgcn_readfirstlane(kdst + (ks) * KSLOT)); \
;         glds16(k2src + (long)(t) * KVBLK * KPP, (unsigned)__builtin_amdgcn_readfirstlane(k2dst + (ks) * KSLOT)); \
;         glds16(vsrc + (long)(t) * KVBLK * VP, (unsigned)__builtin_amdgcn_readfirstlane(vdst + (vs) * VSLOT)); } while (0)
; __device__ __forceinline__ void attn_unit(int b, int h, int qb, const bf16* Q, const bf16* __restrict__ Kn, const bf16* __restrict__ Kpe, const bf16* __restrict__ V, bf16* O, float* ASS, LAS char* shm) {
;     ...
;     const bf16* Qw = Q + (rowbase + q0 + wid * QBLK) * QP + h * 96;
;     const unsigned lds0 = (unsigned)(uintptr_t)shm;
;     LAS float* wsf = (LAS float*)(shm + LDS_WS) + wid * 64;
;     const bf16* ksrc = Kn + (rowbase + lane) * KNP + h * 64 + wid * 8;
;     const bf16* k2src = Kpe + (rowbase + lane) * KPP + (wid & 3) * 8;
;     const bf16* vsrc = V + (rowbase + 16 * (wid & 3) + (lane >> 2)) * VP + h * 64 + (wid >> 2) * 32 + (lane & 3) * 8;
;     const unsigned kdst = lds0 + LDS_K + wid * 1024, k2dst = lds0 + LDS_K + (8 + (wid & 3)) * 1024, vdst = lds0 + LDS_V + wid * 1024;
;     ...
;     const int vb0 = (int)(lds0 + LDS_V) + ((lane >> 4) & 1) * 32 + (lane & 3) * 8 + (4 * hi + ((lane & 15) >> 2)) * 64;
;     const int NT = (q0 + QB) / KVBLK;
;     DMA_TILE(0, 0, 0); DMA_TILE(1, 1, 1);
;     bf16x8 qr[6];
; #pragma unroll
;     for (int d0 = 0; d0 < 6; ++d0) qr[d0] = *reinterpret_cast<const bf16x8*>(&Qw[(long)r32 * QP + d0 * 16 + hi * 8]);
;     asm volatile("" : "+v"(qr[0]), "+v"(qr[1]), "+v"(qr[2]), "+v"(qr[3]), "+v"(qr[4]), "+v"(qr[5]));
;     float m_run = -1e30f, l_run = 0.f; f32x16 o[2]; o[0] = f32x16{}; o[1] = f32x16{};
;     const int qrel = wid * QBLK + r32;
;     f32x16 p0, p1;
;     bf16x8 kf[12]; s16x4 vlo[8], vhi[8]; u32x4 pw0, pw1, pw2, pw3;
;     const LAS char* kp0 = shm + LDS_K + hi * 1024 + r32 * 16;
;     const LAS char* vp0 = shm + LDS_V + ((lane >> 4) & 1) * 32 + (lane & 3) * 8 + (4 * hi + ((lane & 15) >> 2)) * 64;
.LBB0_870:
	v_mov_b32_e32 v138, v163
	s_or_b32 s68, s38, s75
	v_readfirstlane_b32 s4, v138
	s_ashr_i32 s69, s4, 6
	s_lshl_b32 s5, s69, 5
	s_ashr_i32 s38, s5, 31
	s_add_u32 s66, s84, s5
	s_addc_u32 s67, s85, s38
	s_mul_i32 s38, s67, 0x600
	s_mul_hi_u32 s39, s66, 0x600
	s_add_i32 s39, s39, s38
	s_mul_i32 s38, s66, 0x600
	v_and_b32_e32 v139, 63, v138
	s_add_u32 s38, s78, s38
	s_mul_i32 s48, s68, 0x60
	s_addc_u32 s39, s79, s39
	s_lshl_b64 s[64:65], s[48:49], 1
	v_or_b32_e32 v6, s42, v139
	v_mov_b32_e32 v7, s43
	s_add_u32 s38, s38, s64
	s_waitcnt lgkmcnt(0)
	v_lshlrev_b64 v[2:3], 10, v[6:7]
	s_addc_u32 s39, s39, s65
	v_lshl_add_u64 v[2:3], s[0:1], 0, v[2:3]
	s_lshl_b32 s48, s68, 7
	s_lshl_b32 s46, s69, 3
	v_lshl_add_u64 v[2:3], v[2:3], 0, s[48:49]
	s_ashr_i32 s47, s46, 31
	s_and_b32 s50, s69, 3
	v_lshl_add_u64 v[2:3], s[46:47], 1, v[2:3]
	s_lshl_b32 s46, s50, 4
	v_bfe_u32 v0, v138, 2, 4
	v_lshlrev_b64 v[4:5], 6, v[6:7]
	v_or_b32_e32 v0, s46, v0
	v_lshl_add_u64 v[4:5], s[18:19], 0, v[4:5]
	s_mov_b32 s47, s49
	v_or_b32_e32 v6, s42, v0
	v_lshl_add_u64 v[4:5], v[4:5], 0, s[46:47]
	v_lshlrev_b64 v[6:7], 10, v[6:7]
	s_ashr_i32 s46, s4, 3
	v_lshl_add_u64 v[6:7], s[40:41], 0, v[6:7]
	s_andn2_b32 s46, s46, 31
	v_lshl_add_u64 v[6:7], v[6:7], 0, s[48:49]
	s_ashr_i32 s47, s46, 31
	v_lshlrev_b32_e32 v0, 3, v138
	s_lshl_b32 s48, s69, 10
	s_lshl_b32 s50, s50, 10
	v_lshl_add_u64 v[6:7], s[46:47], 1, v[6:7]
	v_and_b32_e32 v10, 24, v0
	s_add_i32 s97, s48, 0
	s_bitset1_b32 s50, 13
	s_mov_b32 s46, m0
	s_mov_b32 m0, s97
	s_nop 0
	global_load_lds_dwordx4 v[2:3], off
	s_mov_b32 m0, s46
	v_lshlrev_b32_e32 v0, 1, v10
	s_add_i32 s72, s50, 0
	s_mov_b32 s46, m0
	s_mov_b32 m0, s72
	s_nop 0
	global_load_lds_dwordx4 v[4:5], off
	s_mov_b32 m0, s46
	v_and_b32_e32 v140, 31, v138
	v_lshl_add_u64 v[6:7], v[6:7], 0, v[0:1]
	s_add_i32 s73, s97, 0x9000
	s_mov_b32 s46, m0
	s_mov_b32 m0, s73
	s_nop 0
	global_load_lds_dwordx4 v[6:7], off
	s_mov_b32 m0, s46
	v_lshl_add_u64 v[8:9], v[2:3], 0, s[34:35]
	s_add_i32 s46, s48, s33
	s_mov_b32 s47, m0
	s_mov_b32 m0, s46
	s_nop 0
	global_load_lds_dwordx4 v[8:9], off
	s_mov_b32 m0, s47
	v_mul_u32_u24_e32 v0, 0x300, v140
	v_bfe_u32 v141, v138, 5, 1
	v_lshl_add_u64 v[8:9], v[4:5], 0, s[20:21]
	s_add_i32 s46, s50, s33
	s_mov_b32 s47, m0
	s_mov_b32 m0, s46
	s_nop 0
	global_load_lds_dwordx4 v[8:9], off
	s_mov_b32 m0, s47
	v_lshlrev_b32_e32 v0, 1, v0
	v_lshl_add_u64 v[8:9], v[6:7], 0, s[34:35]
	s_add_i32 s46, s97, 0xb000
	s_mov_b32 s47, m0
	s_mov_b32 m0, s46
	s_nop 0
	global_load_lds_dwordx4 v[8:9], off
	s_mov_b32 m0, s47
	v_lshl_or_b32 v0, v141, 4, v0
	global_load_dwordx4 v[80:83], v0, s[38:39] offset:160 nt
	global_load_dwordx4 v[84:87], v0, s[38:39] offset:128 nt
	global_load_dwordx4 v[88:91], v0, s[38:39] offset:96 nt
	global_load_dwordx4 v[92:95], v0, s[38:39] offset:64 nt
	global_load_dwordx4 v[96:99], v0, s[38:39] offset:32 nt
	global_load_dwordx4 v[100:103], v0, s[38:39] nt
	s_and_b32 s4, s4, 0x3fffffc0
	v_lshlrev_b32_e32 v0, 1, v138
	s_lshl_b32 s4, s4, 2
	v_lshlrev_b32_e32 v8, 4, v138
	v_and_b32_e32 v0, 32, v0
	s_add_i32 s96, s4, 0
	v_lshlrev_b32_e32 v9, 8, v141
	v_and_b32_e32 v8, 0xc0, v8
	v_lshlrev_b32_e32 v11, 10, v141
	v_lshlrev_b32_e32 v12, 4, v140
	v_add3_u32 v0, 0, v0, v10
	s_add_i32 s96, s96, 0x11000
	v_cmp_gt_u32_e64 s[38:39], 32, v139
	v_lshlrev_b32_e32 v143, 4, v141
	v_add3_u32 v146, 0, v11, v12
	v_or_b32_e32 v145, s5, v140
	v_add3_u32 v144, v0, v9, v8
	v_lshl_add_u64 v[132:133], v[2:3], 0, s[2:3]
	v_lshl_add_u64 v[134:135], v[4:5], 0, s[22:23]
	s_cmp_lt_i32 s69, 4
	v_lshl_add_u32 v142, v140, 2, s96
	v_lshl_add_u64 v[136:137], v[6:7], 0, s[2:3]
	s_mov_b64 s[46:47], -1
	s_waitcnt vmcnt(0)
	s_waitcnt vmcnt(3) lgkmcnt(0)
	s_barrier
	s_add_i32 s4, 0, 0x6000
	v_lshl_add_u64 v[8:9], v[2:3], 0, s[2:3]
	s_add_i32 s48, s48, s4
	s_mov_b32 s5, m0
	s_mov_b32 m0, s48
	s_nop 0
	global_load_lds_dwordx4 v[8:9], off
	s_mov_b32 m0, s5
	v_lshl_add_u64 v[8:9], v[4:5], 0, s[22:23]
	s_add_i32 s50, s50, s4
	s_mov_b32 s4, m0
	s_mov_b32 m0, s50
	s_nop 0
	global_load_lds_dwordx4 v[8:9], off
	s_mov_b32 m0, s4
	v_lshl_add_u64 v[8:9], v[6:7], 0, s[2:3]
	s_add_i32 s4, s97, 0xd000
	s_mov_b32 s5, m0
	s_mov_b32 m0, s4
	s_nop 0
	global_load_lds_dwordx4 v[8:9], off
	s_mov_b32 m0, s5
	ds_read_b128 v[8:11], v146
	ds_read_b128 v[12:15], v146 offset:512
	ds_read_b128 v[16:19], v146 offset:2048
	ds_read_b128 v[20:23], v146 offset:2560
	ds_read_b128 v[24:27], v146 offset:4096
	ds_read_b128 v[28:31], v146 offset:4608
	ds_read_b128 v[32:35], v146 offset:6144
	ds_read_b128 v[36:39], v146 offset:6656
	ds_read_b128 v[40:43], v146 offset:8192
	ds_read_b128 v[44:47], v146 offset:8704
	ds_read_b128 v[104:107], v146 offset:10240
	ds_read_b128 v[108:111], v146 offset:10752
	s_waitcnt lgkmcnt(11)
	v_mfma_f32_32x32x16_bf16 v[64:79], v[8:11], v[100:103], 0
	s_mov_b32 s48, s49
	s_mov_b32 s50, s49
	s_mov_b32 s51, s49
	s_mov_b32 s52, s49
	s_mov_b32 s53, s49
	s_mov_b32 s54, s49
	s_mov_b32 s55, s49
	s_waitcnt lgkmcnt(10)
	v_mfma_f32_32x32x16_bf16 v[48:63], v[12:15], v[100:103], 0
	s_mov_b32 s56, s49
	s_mov_b32 s57, s49
	s_mov_b32 s58, s49
	s_mov_b32 s59, s49
	s_mov_b32 s60, s49
	s_mov_b32 s61, s49
	s_mov_b32 s62, s49
	s_waitcnt lgkmcnt(9)
	v_mfma_f32_32x32x16_bf16 v[64:79], v[16:19], v[96:99], v[64:79]
	s_mov_b32 s63, s49
	s_waitcnt lgkmcnt(8)
	v_mfma_f32_32x32x16_bf16 v[48:63], v[20:23], v[96:99], v[48:63]
	s_waitcnt lgkmcnt(7)
	v_mfma_f32_32x32x16_bf16 v[64:79], v[24:27], v[92:95], v[64:79]
	s_waitcnt lgkmcnt(6)
	v_mfma_f32_32x32x16_bf16 v[48:63], v[28:31], v[92:95], v[48:63]
	v_mov_b64_e32 v[16:17], s[48:49]
	v_mov_b64_e32 v[18:19], s[50:51]
	v_mov_b64_e32 v[20:21], s[52:53]
	v_mov_b64_e32 v[22:23], s[54:55]
	v_mov_b64_e32 v[24:25], s[56:57]
	v_mov_b64_e32 v[26:27], s[58:59]
	v_mov_b64_e32 v[28:29], s[60:61]
	s_waitcnt lgkmcnt(5)
	v_mfma_f32_32x32x16_bf16 v[64:79], v[32:35], v[88:91], v[64:79]
	v_mov_b64_e32 v[30:31], s[62:63]
	s_waitcnt lgkmcnt(4)
	v_mfma_f32_32x32x16_bf16 v[48:63], v[36:39], v[88:91], v[48:63]
	s_waitcnt lgkmcnt(3)
	v_mfma_f32_32x32x16_bf16 v[64:79], v[40:43], v[84:87], v[64:79]
	s_waitcnt lgkmcnt(2)
	v_mfma_f32_32x32x16_bf16 v[48:63], v[44:47], v[84:87], v[48:63]
	s_waitcnt lgkmcnt(1)
	v_mfma_f32_32x32x16_bf16 v[64:79], v[104:107], v[80:83], v[64:79]
	s_waitcnt lgkmcnt(0)
	v_mfma_f32_32x32x16_bf16 v[48:63], v[108:111], v[80:83], v[48:63]
	s_mov_b64 s[4:5], 0x30000
	v_mov_b64_e32 v[46:47], v[30:31]
	v_lshl_add_u32 v0, v141, 2, s92
	v_lshl_add_u64 v[14:15], v[4:5], 0, s[6:7]
	v_lshl_add_u64 v[124:125], v[6:7], 0, s[4:5]
	v_lshl_add_u64 v[126:127], v[2:3], 0, s[4:5]
	s_mov_b32 s48, 1
	v_mov_b32_e32 v128, 0
	v_mov_b32_e32 v130, 0xf149f2ca
	v_mov_b64_e32 v[44:45], v[28:29]
	v_mov_b64_e32 v[42:43], v[26:27]
	v_mov_b64_e32 v[40:41], v[24:25]
	v_mov_b64_e32 v[38:39], v[22:23]
	v_mov_b64_e32 v[36:37], v[20:21]
	v_mov_b64_e32 v[34:35], v[18:19]
	v_mov_b64_e32 v[32:33], v[16:17]
	s_mov_b32 s50, 1
	s_mov_b32 s52, 1
	s_add_i32 s51, s52, 1
	s_cmp_ge_u32 s51, s86
	s_mov_b64 s[46:47], -1
	s_branch .Lat_u1_entry

; #define LAS __attribute__((address_space(3)))
; #define DMA_TILE(t, ks, vs) do { glds16(ksrc + (long)(t) * KVBLK * KNP, (unsigned)__builtin_amdgcn_readfirstlane(kdst + (ks) * KSLOT)); \
;         glds16(k2src + (long)(t) * KVBLK * KPP, (unsigned)__builtin_amdgcn_readfirstlane(k2dst + (ks) * KSLOT)); \
;         glds16(vsrc + (long)(t) * KVBLK * VP, (unsigned)__builtin_amdgcn_readfirstlane(vdst + (vs) * VSLOT)); } while (0)
; __device__ __forceinline__ void attn_unit(int b, int h, int qb, const bf16* Q, const bf16* __restrict__ Kn, const bf16* __restrict__ Kpe, const bf16* __restrict__ V, bf16* O, float* ASS, LAS char* shm) {
;     ...
;     const bf16* Qw = Q + (rowbase + q0 + wid * QBLK) * QP + h * 96;
;     const unsigned lds0 = (unsigned)(uintptr_t)shm;
;     LAS float* wsf = (LAS float*)(shm + LDS_WS) + wid * 64;
;     const bf16* ksrc = Kn + (rowbase + lane) * KNP + h * 64 + wid * 8;
;     const bf16* k2src = Kpe + (rowbase + lane) * KPP + (wid & 3) * 8;
;     const bf16* vsrc = V + (rowbase + 16 * (wid & 3) + (lane >> 2)) * VP + h * 64 + (wid >> 2) * 32 + (lane & 3) * 8;
;     const unsigned kdst = lds0 + LDS_K + wid * 1024, k2dst = lds0 + LDS_K + (8 + (wid & 3)) * 1024, vdst = lds0 + LDS_V + wid * 1024;
;     ...
;     const int vb0 = (int)(lds0 + LDS_V) + ((lane >> 4) & 1) * 32 + (lane & 3) * 8 + (4 * hi + ((lane & 15) >> 2)) * 64;
;     const int NT = (q0 + QB) / KVBLK;
;     DMA_TILE(0, 0, 0); DMA_TILE(1, 1, 1);
;     bf16x8 qr[6];
; #pragma unroll
;     for (int d0 = 0; d0 < 6; ++d0) qr[d0] = *reinterpret_cast<const bf16x8*>(&Qw[(long)r32 * QP + d0 * 16 + hi * 8]);
.LBB0_915:
	s_or_b64 exec, exec, s[38:39]
	v_mov_b32_e32 v139, v163
	s_waitcnt lgkmcnt(0)
	s_barrier
	v_mov_b32_e32 v3, s43
	v_readfirstlane_b32 s4, v139
	s_ashr_i32 s56, s4, 6
	s_lshl_b32 s5, s56, 5
	s_ashr_i32 s38, s5, 31
	s_add_u32 s52, s88, s5
	s_addc_u32 s53, s89, s38
	s_mul_i32 s38, s53, 0x600
	s_mul_hi_u32 s39, s52, 0x600
	s_add_i32 s39, s39, s38
	s_mul_i32 s38, s52, 0x600
	v_and_b32_e32 v140, 63, v139
	s_add_u32 s38, s78, s38
	s_addc_u32 s39, s79, s39
	s_waitcnt lgkmcnt(0)
	v_or_b32_e32 v2, s42, v140
	s_add_u32 s38, s38, s64
	v_lshlrev_b64 v[4:5], 10, v[2:3]
	s_addc_u32 s39, s39, s65
	v_lshl_add_u64 v[4:5], s[0:1], 0, v[4:5]
	s_lshl_b32 s54, s56, 3
	v_lshl_add_u64 v[4:5], v[4:5], 0, s[48:49]
	s_ashr_i32 s55, s54, 31
	s_and_b32 s57, s56, 3
	v_lshl_add_u64 v[90:91], s[54:55], 1, v[4:5]
	s_lshl_b32 s54, s57, 4
	v_bfe_u32 v0, v139, 2, 4
	v_lshlrev_b64 v[4:5], 6, v[2:3]
	v_or_b32_e32 v0, s54, v0
	v_lshl_add_u64 v[4:5], s[18:19], 0, v[4:5]
	s_mov_b32 s55, s49
	v_or_b32_e32 v2, s42, v0
	v_lshl_add_u64 v[92:93], v[4:5], 0, s[54:55]
	v_lshlrev_b64 v[2:3], 10, v[2:3]
	s_ashr_i32 s54, s4, 3
	v_lshl_add_u64 v[2:3], s[40:41], 0, v[2:3]
	s_andn2_b32 s54, s54, 31
	v_lshl_add_u64 v[2:3], v[2:3], 0, s[48:49]
	s_ashr_i32 s55, s54, 31
	v_lshl_add_u64 v[2:3], s[54:55], 1, v[2:3]
	v_lshlrev_b32_e32 v0, 3, v139
	s_lshl_b32 s54, s56, 10
	s_lshl_b32 s55, s57, 10
	v_and_b32_e32 v4, 24, v0
	s_add_i32 s58, s54, 0
	s_bitset1_b32 s55, 13
	s_mov_b32 s57, m0
	s_mov_b32 m0, s58
	s_nop 0
	global_load_lds_dwordx4 v[90:91], off
	s_mov_b32 m0, s57
	v_lshlrev_b32_e32 v0, 1, v4
	s_add_i32 s59, s55, 0
	s_mov_b32 s57, m0
	s_mov_b32 m0, s59
	s_nop 0
	global_load_lds_dwordx4 v[92:93], off
	s_mov_b32 m0, s57
	v_and_b32_e32 v141, 31, v139
	v_lshl_add_u64 v[94:95], v[2:3], 0, v[0:1]
	s_add_i32 s60, s58, 0x9000
	s_mov_b32 s57, m0
	s_mov_b32 m0, s60
	s_nop 0
	global_load_lds_dwordx4 v[94:95], off
	s_mov_b32 m0, s57
	v_lshl_add_u64 v[2:3], v[90:91], 0, s[34:35]
	s_add_i32 s57, s54, s33
	s_mov_b32 s61, m0
	s_mov_b32 m0, s57
	s_nop 0
	global_load_lds_dwordx4 v[2:3], off
	s_mov_b32 m0, s61
	v_mul_u32_u24_e32 v0, 0x300, v141
	v_bfe_u32 v142, v139, 5, 1
	v_lshl_add_u64 v[2:3], v[92:93], 0, s[20:21]
	s_add_i32 s57, s55, s33
	s_mov_b32 s61, m0
	s_mov_b32 m0, s57
	s_nop 0
	global_load_lds_dwordx4 v[2:3], off
	s_mov_b32 m0, s61
	v_lshlrev_b32_e32 v0, 1, v0
	v_lshl_add_u64 v[2:3], v[94:95], 0, s[34:35]
	s_add_i32 s57, s58, 0xb000
	s_mov_b32 s61, m0
	s_mov_b32 m0, s57
	s_nop 0
	global_load_lds_dwordx4 v[2:3], off
	s_mov_b32 m0, s61
	v_lshl_or_b32 v0, v142, 4, v0
	global_load_dwordx4 v[66:69], v0, s[38:39] offset:160 nt
	global_load_dwordx4 v[70:73], v0, s[38:39] offset:128 nt
	global_load_dwordx4 v[74:77], v0, s[38:39] offset:96 nt
	global_load_dwordx4 v[78:81], v0, s[38:39] offset:64 nt
	global_load_dwordx4 v[82:85], v0, s[38:39] offset:32 nt
	global_load_dwordx4 v[86:89], v0, s[38:39] nt
	s_and_b32 s4, s4, 0x3fffffc0
	v_lshlrev_b32_e32 v0, 1, v139
	s_lshl_b32 s4, s4, 2
	v_lshlrev_b32_e32 v2, 4, v139
	v_and_b32_e32 v0, 32, v0
	s_add_i32 s57, s4, 0
	v_lshlrev_b32_e32 v3, 8, v142
	v_and_b32_e32 v2, 0xc0, v2
	v_lshlrev_b32_e32 v5, 10, v142
	v_lshlrev_b32_e32 v6, 4, v141
	v_add3_u32 v0, 0, v0, v4
	s_add_i32 s57, s57, 0x11000
	s_mov_b64 s[38:39], -1
	v_lshlrev_b32_e32 v144, 2, v142
	v_add3_u32 v146, 0, v5, v6
	v_or_b32_e32 v145, s5, v141
	v_add3_u32 v143, v0, v3, v2
	v_lshl_add_u64 v[130:131], v[90:91], 0, s[2:3]
	v_lshl_add_u64 v[132:133], v[92:93], 0, s[22:23]
	s_cmp_lt_i32 s56, 4
	v_lshl_add_u64 v[134:135], v[94:95], 0, s[2:3]
	s_waitcnt vmcnt(0)
	s_waitcnt vmcnt(3) lgkmcnt(0)
	s_barrier
; __device__ __forceinline__ void cmask(f32x16& p0, f32x16& p1, int jb, int qrel, int hi) {
;     const float NEG = -INFINITY; const int kb = 64 * jb + 4 * hi;
; #pragma unroll
;     for (int r = 0; r < 16; ++r) { const int kv = kb + (r & 3) + 8 * (r >> 2); if (kv > qrel) p0[r] = NEG; if (kv + 32 > qrel) p1[r] = NEG; }
; }
	s_add_i32 s4, 0, 0x6000
	v_lshl_add_u64 v[2:3], v[90:91], 0, s[2:3]
	s_add_i32 s54, s54, s4
	s_mov_b32 s5, m0
	s_mov_b32 m0, s54
	s_nop 0
	global_load_lds_dwordx4 v[2:3], off
	s_mov_b32 m0, s5
	v_lshl_add_u64 v[2:3], v[92:93], 0, s[22:23]
	s_add_i32 s55, s55, s4
	s_mov_b32 s4, m0
	s_mov_b32 m0, s55
	s_nop 0
	global_load_lds_dwordx4 v[2:3], off
	s_mov_b32 m0, s4
	v_lshl_add_u64 v[2:3], v[94:95], 0, s[2:3]
	s_add_i32 s4, s58, 0xd000
	s_mov_b32 s5, m0
	s_mov_b32 m0, s4
	s_nop 0
	global_load_lds_dwordx4 v[2:3], off
	s_mov_b32 m0, s5
	ds_read_b128 v[2:5], v146
	ds_read_b128 v[6:9], v146 offset:512
	ds_read_b128 v[10:13], v146 offset:2048
	ds_read_b128 v[14:17], v146 offset:2560
	ds_read_b128 v[18:21], v146 offset:4096
	ds_read_b128 v[22:25], v146 offset:4608
	ds_read_b128 v[26:29], v146 offset:6144
	ds_read_b128 v[30:33], v146 offset:6656
	ds_read_b128 v[96:99], v146 offset:8192
	ds_read_b128 v[100:103], v146 offset:8704
	ds_read_b128 v[104:107], v146 offset:10240
	ds_read_b128 v[108:111], v146 offset:10752
	s_waitcnt lgkmcnt(11)
	v_mfma_f32_32x32x16_bf16 v[50:65], v[2:5], v[86:89], 0
	s_andn2_b64 vcc, exec, s[44:45]
	s_waitcnt lgkmcnt(10)
	v_mfma_f32_32x32x16_bf16 v[34:49], v[6:9], v[86:89], 0
	s_waitcnt lgkmcnt(9)
	v_mfma_f32_32x32x16_bf16 v[50:65], v[10:13], v[82:85], v[50:65]
	s_waitcnt lgkmcnt(8)
	v_mfma_f32_32x32x16_bf16 v[34:49], v[14:17], v[82:85], v[34:49]
	s_waitcnt lgkmcnt(7)
	v_mfma_f32_32x32x16_bf16 v[50:65], v[18:21], v[78:81], v[50:65]
	s_waitcnt lgkmcnt(6)
	v_mfma_f32_32x32x16_bf16 v[34:49], v[22:25], v[78:81], v[34:49]
	s_waitcnt lgkmcnt(5)
	v_mfma_f32_32x32x16_bf16 v[50:65], v[26:29], v[74:77], v[50:65]
	s_waitcnt lgkmcnt(4)
	v_mfma_f32_32x32x16_bf16 v[34:49], v[30:33], v[74:77], v[34:49]
	s_waitcnt lgkmcnt(3)
	v_mfma_f32_32x32x16_bf16 v[50:65], v[96:99], v[70:73], v[50:65]
	s_waitcnt lgkmcnt(2)
	v_mfma_f32_32x32x16_bf16 v[34:49], v[100:103], v[70:73], v[34:49]
	s_waitcnt lgkmcnt(1)
	v_mfma_f32_32x32x16_bf16 v[50:65], v[104:107], v[66:69], v[50:65]
	s_waitcnt lgkmcnt(0)
	v_mfma_f32_32x32x16_bf16 v[34:49], v[108:111], v[66:69], v[34:49]
	s_cbranch_vccnz .LBB0_918
	v_or_b32_e32 v0, 32, v144
	v_cmp_le_i32_e32 vcc, v0, v145
	v_or_b32_e32 v0, 33, v144
	s_nop 7
	v_cndmask_b32_e32 v34, v220, v34, vcc
	v_cmp_lt_i32_e32 vcc, v144, v145
	s_nop 1
	v_cndmask_b32_e32 v51, v220, v51, vcc
	v_cmp_le_i32_e32 vcc, v144, v145
	s_nop 1
	v_cndmask_b32_e32 v50, v220, v50, vcc
	v_cmp_le_i32_e32 vcc, v0, v145
	v_or_b32_e32 v0, 2, v144
	s_nop 0
	v_cndmask_b32_e32 v35, v220, v35, vcc
	v_cmp_le_i32_e32 vcc, v0, v145
	v_or_b32_e32 v0, 34, v144
	s_nop 0
	v_cndmask_b32_e32 v52, v220, v52, vcc
	v_cmp_le_i32_e32 vcc, v0, v145
	v_or_b32_e32 v0, 3, v144
	s_nop 0
	v_cndmask_b32_e32 v36, v220, v36, vcc
	v_cmp_le_i32_e32 vcc, v0, v145
	v_or_b32_e32 v0, 35, v144
	s_nop 0
	v_cndmask_b32_e32 v53, v220, v53, vcc
	v_cmp_le_i32_e32 vcc, v0, v145
	v_or_b32_e32 v0, 8, v144
	s_nop 0
	v_cndmask_b32_e32 v37, v220, v37, vcc
	v_cmp_le_i32_e32 vcc, v0, v145
	v_or_b32_e32 v0, 40, v144
	s_nop 0
	v_cndmask_b32_e32 v54, v220, v54, vcc
	v_cmp_le_i32_e32 vcc, v0, v145
	v_or_b32_e32 v0, 9, v144
	s_nop 0
	v_cndmask_b32_e32 v38, v220, v38, vcc
	v_cmp_le_i32_e32 vcc, v0, v145
	v_or_b32_e32 v0, 41, v144
	s_nop 0
	v_cndmask_b32_e32 v55, v220, v55, vcc
	v_cmp_le_i32_e32 vcc, v0, v145
	v_or_b32_e32 v0, 10, v144
	s_nop 0
	v_cndmask_b32_e32 v39, v220, v39, vcc
	v_cmp_le_i32_e32 vcc, v0, v145
	v_or_b32_e32 v0, 42, v144
	s_nop 0
	v_cndmask_b32_e32 v56, v220, v56, vcc
	v_cmp_le_i32_e32 vcc, v0, v145
	v_or_b32_e32 v0, 11, v144
	s_nop 0
	v_cndmask_b32_e32 v40, v220, v40, vcc
	v_cmp_le_i32_e32 vcc, v0, v145
	v_or_b32_e32 v0, 43, v144
	s_nop 0
	v_cndmask_b32_e32 v57, v220, v57, vcc
	v_cmp_le_i32_e32 vcc, v0, v145
	v_or_b32_e32 v0, 16, v144
	s_nop 0
	v_cndmask_b32_e32 v41, v220, v41, vcc
	v_cmp_le_i32_e32 vcc, v0, v145
	v_or_b32_e32 v0, 48, v144
	s_nop 0
	v_cndmask_b32_e32 v58, v220, v58, vcc
	v_cmp_le_i32_e32 vcc, v0, v145
	v_or_b32_e32 v0, 17, v144
	s_nop 0
	v_cndmask_b32_e32 v42, v220, v42, vcc
	v_cmp_le_i32_e32 vcc, v0, v145
	v_or_b32_e32 v0, 49, v144
	s_nop 0
	v_cndmask_b32_e32 v59, v220, v59, vcc
	v_cmp_le_i32_e32 vcc, v0, v145
	v_or_b32_e32 v0, 18, v144
	s_nop 0
	v_cndmask_b32_e32 v43, v220, v43, vcc
	v_cmp_le_i32_e32 vcc, v0, v145
	v_or_b32_e32 v0, 50, v144
	s_nop 0
	v_cndmask_b32_e32 v60, v220, v60, vcc
	v_cmp_le_i32_e32 vcc, v0, v145
	v_or_b32_e32 v0, 19, v144
	s_nop 0
	v_cndmask_b32_e32 v44, v220, v44, vcc
	v_cmp_le_i32_e32 vcc, v0, v145
	v_or_b32_e32 v0, 51, v144
	s_nop 0
	v_cndmask_b32_e32 v61, v220, v61, vcc
	v_cmp_le_i32_e32 vcc, v0, v145
	v_or_b32_e32 v0, 24, v144
	s_nop 0
	v_cndmask_b32_e32 v45, v220, v45, vcc
	v_cmp_le_i32_e32 vcc, v0, v145
	v_or_b32_e32 v0, 56, v144
	s_nop 0
	v_cndmask_b32_e32 v62, v220, v62, vcc
	v_cmp_le_i32_e32 vcc, v0, v145
	v_or_b32_e32 v0, 25, v144
	s_nop 0
	v_cndmask_b32_e32 v46, v220, v46, vcc
	v_cmp_le_i32_e32 vcc, v0, v145
	v_or_b32_e32 v0, 57, v144
	s_nop 0
	v_cndmask_b32_e32 v63, v220, v63, vcc
	v_cmp_le_i32_e32 vcc, v0, v145
	v_or_b32_e32 v0, 26, v144
	s_nop 0
	v_cndmask_b32_e32 v47, v220, v47, vcc
	v_cmp_le_i32_e32 vcc, v0, v145
	v_or_b32_e32 v0, 58, v144
	s_nop 0
	v_cndmask_b32_e32 v64, v220, v64, vcc
	v_cmp_le_i32_e32 vcc, v0, v145
	v_or_b32_e32 v0, 27, v144
	s_nop 0
	v_cndmask_b32_e32 v48, v220, v48, vcc
	v_cmp_le_i32_e32 vcc, v0, v145
	v_or_b32_e32 v0, 59, v144
	s_nop 0
	v_cndmask_b32_e32 v65, v220, v65, vcc
	v_cmp_le_i32_e32 vcc, v0, v145
	s_nop 1
	v_cndmask_b32_e32 v49, v220, v49, vcc
